# v29 + touch-prefetch of the mLSTM output unit's conv input rows (warms L1/L2 before the serialized tap loads)
# baseline (speedup 1.0000x reference)
; __device__ __forceinline__ float bflo(unsigned w) { return __uint_as_float(w << 16); }
; __device__ __forceinline__ float bfhi(unsigned w) { return __uint_as_float(w & 0xffff0000u); }
; __device__ __forceinline__ void conv_silu8(const bf16_t* __restrict__ PROJ, const float* __restrict__ cw, const float* __restrict__ cb, int row, int ch, float (&y)[8]) {
;     const f32x4 b0 = *(const f32x4*)(cb + ch), b1 = *(const f32x4*)(cb + ch + 4);
;     float a[8] = {b0[0], b0[1], b0[2], b0[3], b1[0], b1[1], b1[2], b1[3]};
; #pragma unroll
;     for (int k = 0; k < 4; ++k) { const int rr = row - 3 + k;
;         if (rr >= 0) { const u32x4 x = *(const u32x4*)(PROJ + (size_t)rr * PW + ch);
;             const f32x4 w0 = *(const f32x4*)(cw + k * 1024 + ch), w1 = *(const f32x4*)(cw + k * 1024 + ch + 4);
;             a[0] += w0[0] * bflo(x.x); a[1] += w0[1] * bfhi(x.x); a[2] += w0[2] * bflo(x.y); a[3] += w0[3] * bfhi(x.y);
;             a[4] += w1[0] * bflo(x.z); a[5] += w1[1] * bfhi(x.z); a[6] += w1[2] * bflo(x.w); a[7] += w1[3] * bfhi(x.w); } }
; __device__ __forceinline__ void mlstm_out_unit(const Params& P, int l, int h, int n, char* lds) {
;     ...
;     for (int i = 0; i < 4; ++i) { const int idx = tid + 512 * i, which = idx >> 10, t = (idx >> 4) & 63, c = idx & 15; float y[8];
;         conv_silu8(PROJ, cw, cb, t0 + t, which * 512 + h * 128 + c * 8, y);
.LBB0_981:
	s_waitcnt lgkmcnt(0)
	s_add_u32 s14, s40, 0xeb00000
	v_lshlrev_b32_e32 v15, 3, v20
	v_ashrrev_i32_e32 v2, 1, v20
	s_addc_u32 s15, s41, 0
	s_lshl_b32 s22, s66, 7
	v_and_b32_e32 v17, 0x78, v15
	v_and_b32_e32 v2, 0xfffffe00, v2
	v_or3_b32 v10, s22, v2, v17
	v_ashrrev_i32_e32 v11, 31, v10
	v_lshlrev_b64 v[22:23], 2, v[10:11]
	v_lshl_add_u64 v[2:3], s[18:19], 0, v[22:23]
	flat_load_dwordx4 v[6:9], v[2:3]
	s_nop 0
	flat_load_dwordx4 v[2:5], v[2:3] offset:16
	v_bfe_u32 v16, v20, 4, 6
	v_or_b32_e32 v19, s64, v16
	v_lshl_add_u64 v[12:13], v[10:11], 1, s[14:15]
	v_lshl_add_u64 v[10:11], s[16:17], 0, v[22:23]
	v_cmp_lt_i32_e64 s[6:7], 2, v19
	v_add_u32_e32 v22, -3, v19
	v_max_i32_e32 v200, 0, v22
	v_add_u32_e32 v201, 32, v200
	s_mov_b32 s98, 0x3000
	s_mov_b32 s99, 0
	v_mad_u64_u32 v[196:197], s[100:101], v200, s50, v[12:13]
	v_mad_u64_u32 v[198:199], s[100:101], v201, s50, v[12:13]
	global_load_dword v200, v[196:197], off
	global_load_dword v201, v[196:197], off offset:1024
	global_load_dword v202, v[198:199], off
	global_load_dword v203, v[198:199], off offset:1024
	v_lshl_add_u64 v[196:197], v[196:197], 0, s[98:99]
	v_lshl_add_u64 v[198:199], v[198:199], 0, s[98:99]
	global_load_dword v204, v[196:197], off
	global_load_dword v205, v[196:197], off offset:1024
	global_load_dword v206, v[198:199], off
	global_load_dword v207, v[198:199], off offset:1024
	v_lshl_add_u64 v[196:197], v[196:197], 0, s[98:99]
	v_lshl_add_u64 v[198:199], v[198:199], 0, s[98:99]
	global_load_dword v208, v[196:197], off
	global_load_dword v209, v[196:197], off offset:1024
	global_load_dword v210, v[198:199], off
	global_load_dword v211, v[198:199], off offset:1024
	v_lshl_add_u64 v[196:197], v[196:197], 0, s[98:99]
	v_lshl_add_u64 v[198:199], v[198:199], 0, s[98:99]
	global_load_dword v212, v[196:197], off
	global_load_dword v213, v[196:197], off offset:1024
	global_load_dword v214, v[198:199], off
	global_load_dword v215, v[198:199], off offset:1024
	s_and_saveexec_b64 s[8:9], s[6:7]
	s_cbranch_execz .LBB0_983
	v_mad_u64_u32 v[24:25], s[10:11], v22, s50, v[12:13]
	flat_load_dwordx4 v[24:27], v[24:25]
	s_nop 0
	flat_load_dwordx4 v[28:31], v[10:11]
	flat_load_dwordx4 v[32:35], v[10:11] offset:16
	s_waitcnt vmcnt(0) lgkmcnt(0)
	v_lshlrev_b32_e32 v36, 16, v24
	v_and_b32_e32 v37, 0xffff0000, v24
	v_lshlrev_b32_e32 v24, 16, v25
	v_and_b32_e32 v25, 0xffff0000, v25
	v_lshlrev_b32_e32 v38, 16, v26
	v_and_b32_e32 v39, 0xffff0000, v26
	v_lshlrev_b32_e32 v26, 16, v27
	v_and_b32_e32 v27, 0xffff0000, v27
	v_pk_fma_f32 v[6:7], v[28:29], v[36:37], v[6:7]
	v_pk_fma_f32 v[8:9], v[30:31], v[24:25], v[8:9]
	v_pk_fma_f32 v[2:3], v[32:33], v[38:39], v[2:3]
	v_pk_fma_f32 v[4:5], v[34:35], v[26:27], v[4:5]

; __device__ __forceinline__ float bflo(unsigned w) { return __uint_as_float(w << 16); }
; __device__ __forceinline__ float bfhi(unsigned w) { return __uint_as_float(w & 0xffff0000u); }
; __device__ __forceinline__ void conv_silu8(const bf16_t* __restrict__ PROJ, const float* __restrict__ cw, const float* __restrict__ cb, int row, int ch, float (&y)[8]) {
;     const f32x4 b0 = *(const f32x4*)(cb + ch), b1 = *(const f32x4*)(cb + ch + 4);
;     float a[8] = {b0[0], b0[1], b0[2], b0[3], b1[0], b1[1], b1[2], b1[3]};
; #pragma unroll
;     for (int k = 0; k < 4; ++k) { const int rr = row - 3 + k;
;         if (rr >= 0) { const u32x4 x = *(const u32x4*)(PROJ + (size_t)rr * PW + ch);
;             const f32x4 w0 = *(const f32x4*)(cw + k * 1024 + ch), w1 = *(const f32x4*)(cw + k * 1024 + ch + 4);
;             a[0] += w0[0] * bflo(x.x); a[1] += w0[1] * bfhi(x.x); a[2] += w0[2] * bflo(x.y); a[3] += w0[3] * bfhi(x.y);
;             a[4] += w1[0] * bflo(x.z); a[5] += w1[1] * bfhi(x.z); a[6] += w1[2] * bflo(x.w); a[7] += w1[3] * bfhi(x.w); } }
; __device__ __forceinline__ void mlstm_out_unit(const Params& P, int l, int h, int n, char* lds) {
;     ...
;     for (int i = 0; i < 4; ++i) { const int idx = tid + 512 * i, which = idx >> 10, t = (idx >> 4) & 63, c = idx & 15; float y[8];
;         conv_silu8(PROJ, cw, cb, t0 + t, which * 512 + h * 128 + c * 8, y);
.LBB0_2409:
	s_waitcnt lgkmcnt(0)
	s_add_u32 s14, s40, 0xeb00000
	s_addc_u32 s15, s41, 0
	s_add_u32 s16, s16, 0x4000
	s_addc_u32 s17, s17, 0
	s_add_u32 s18, s18, 0x1000
	v_lshlrev_b32_e32 v15, 3, v20
	v_ashrrev_i32_e32 v2, 1, v20
	s_addc_u32 s19, s19, 0
	s_lshl_b32 s22, s66, 7
	v_and_b32_e32 v17, 0x78, v15
	v_and_b32_e32 v2, 0xfffffe00, v2
	v_or3_b32 v10, s22, v2, v17
	v_ashrrev_i32_e32 v11, 31, v10
	v_lshlrev_b64 v[22:23], 2, v[10:11]
	v_lshl_add_u64 v[2:3], s[18:19], 0, v[22:23]
	flat_load_dwordx4 v[6:9], v[2:3]
	s_nop 0
	flat_load_dwordx4 v[2:5], v[2:3] offset:16
	v_bfe_u32 v16, v20, 4, 6
	v_or_b32_e32 v19, s64, v16
	v_lshl_add_u64 v[12:13], v[10:11], 1, s[14:15]
	v_lshl_add_u64 v[10:11], s[16:17], 0, v[22:23]
	v_cmp_lt_i32_e64 s[6:7], 2, v19
	v_add_u32_e32 v22, -3, v19
	v_max_i32_e32 v200, 0, v22
	v_add_u32_e32 v201, 32, v200
	s_mov_b32 s98, 0x3000
	s_mov_b32 s99, 0
	v_mad_u64_u32 v[196:197], s[100:101], v200, s50, v[12:13]
	v_mad_u64_u32 v[198:199], s[100:101], v201, s50, v[12:13]
	global_load_dword v200, v[196:197], off
	global_load_dword v201, v[196:197], off offset:1024
	global_load_dword v202, v[198:199], off
	global_load_dword v203, v[198:199], off offset:1024
	v_lshl_add_u64 v[196:197], v[196:197], 0, s[98:99]
	v_lshl_add_u64 v[198:199], v[198:199], 0, s[98:99]
	global_load_dword v204, v[196:197], off
	global_load_dword v205, v[196:197], off offset:1024
	global_load_dword v206, v[198:199], off
	global_load_dword v207, v[198:199], off offset:1024
	v_lshl_add_u64 v[196:197], v[196:197], 0, s[98:99]
	v_lshl_add_u64 v[198:199], v[198:199], 0, s[98:99]
	global_load_dword v208, v[196:197], off
	global_load_dword v209, v[196:197], off offset:1024
	global_load_dword v210, v[198:199], off
	global_load_dword v211, v[198:199], off offset:1024
	v_lshl_add_u64 v[196:197], v[196:197], 0, s[98:99]
	v_lshl_add_u64 v[198:199], v[198:199], 0, s[98:99]
	global_load_dword v212, v[196:197], off
	global_load_dword v213, v[196:197], off offset:1024
	global_load_dword v214, v[198:199], off
	global_load_dword v215, v[198:199], off offset:1024
	s_and_saveexec_b64 s[8:9], s[6:7]
	s_cbranch_execz .LBB0_2411
	v_mad_u64_u32 v[24:25], s[10:11], v22, s50, v[12:13]
	flat_load_dwordx4 v[24:27], v[24:25]
	s_nop 0
	flat_load_dwordx4 v[28:31], v[10:11]
	flat_load_dwordx4 v[32:35], v[10:11] offset:16
	s_waitcnt vmcnt(0) lgkmcnt(0)
	v_lshlrev_b32_e32 v36, 16, v24
	v_and_b32_e32 v37, 0xffff0000, v24
	v_lshlrev_b32_e32 v24, 16, v25
	v_and_b32_e32 v25, 0xffff0000, v25
	v_lshlrev_b32_e32 v38, 16, v26
	v_and_b32_e32 v39, 0xffff0000, v26
	v_lshlrev_b32_e32 v26, 16, v27
	v_and_b32_e32 v27, 0xffff0000, v27
	v_pk_fma_f32 v[6:7], v[28:29], v[36:37], v[6:7]
	v_pk_fma_f32 v[8:9], v[30:31], v[24:25], v[8:9]
	v_pk_fma_f32 v[2:3], v[32:33], v[38:39], v[2:3]
	v_pk_fma_f32 v[4:5], v[34:35], v[26:27], v[4:5]
